# v9 + P0 weight transposes read the f32 weights with non-temporal loads
# speedup vs baseline: 1.0084x; 1.0084x over previous
; template <int MODE>
; __device__ __forceinline__ void transpose_item(const float* W, int K, int N, bf16_t* WT, const float* gain, LAS float* scr, int item, int lane) {
;     const int nblk = N / 32, kb = item / nblk, nb = item % nblk, k0 = 64 * kb, n0 = 32 * nb;
; #pragma unroll 8
;     for (int i = 0; i < 32; ++i) { const int kk = 2 * i + (lane >> 5); float w = W[(size_t)(k0 + kk) * N + n0 + (lane & 31)]; if (MODE == 0) w *= gain[k0 + kk]; scr[kk * 33 + (lane & 31)] = w; }
.LBB0_58:
	s_lshl_b32 s29, s26, 1
	s_lshl_b32 s30, s27, 1
	v_or_b32_e32 v17, s29, v1
	v_or_b32_e32 v48, s30, v2
	s_add_i32 s33, s30, 4
	s_add_i32 s31, s29, 4
	s_add_i32 s34, s29, 8
	s_add_i32 s35, s30, 8
	s_add_i32 s36, s29, 12
	s_add_i32 s38, s29, 16
	s_add_i32 s40, s29, 20
	s_add_i32 s42, s29, 24
	s_add_i32 s29, s29, 28
	v_add_lshl_u32 v4, v17, s3, 9
	v_add_lshl_u32 v22, v48, s3, 9
	v_or_b32_e32 v50, s33, v2
	s_add_i32 s37, s30, 12
	v_or_b32_e32 v49, s31, v1
	v_or_b32_e32 v51, s34, v1
	v_or_b32_e32 v52, s35, v2
	v_or_b32_e32 v53, s36, v1
	v_or_b32_e32 v55, s38, v1
	v_or_b32_e32 v57, s40, v1
	v_or_b32_e32 v59, s42, v1
	v_or_b32_e32 v61, s29, v1
	v_or_b32_e32 v20, v3, v4
	v_or_b32_e32 v4, v16, v22
	v_add_lshl_u32 v32, v50, s3, 9
	v_mov_b32_e32 v21, v5
	s_add_i32 s39, s30, 16
	v_or_b32_e32 v54, s37, v2
	v_add_lshl_u32 v22, v49, s3, 9
	v_add_lshl_u32 v34, v51, s3, 9
	v_add_lshl_u32 v63, v52, s3, 9
	v_add_lshl_u32 v36, v53, s3, 9
	v_add_lshl_u32 v38, v55, s3, 9
	v_add_lshl_u32 v40, v57, s3, 9
	v_add_lshl_u32 v42, v59, s3, 9
	v_add_lshl_u32 v46, v61, s3, 9
	v_lshl_add_u64 v[44:45], v[4:5], 2, s[68:69]
	v_or_b32_e32 v4, v16, v32
	v_mov_b32_e32 v23, v5
	s_add_i32 s41, s30, 20
	v_or_b32_e32 v56, s39, v2
	v_add_lshl_u32 v64, v54, s3, 9
	v_lshl_add_u64 v[20:21], v[20:21], 2, s[68:69]
	v_or_b32_e32 v22, v3, v22
	v_or_b32_e32 v32, v3, v34
	v_or_b32_e32 v34, v3, v36
	v_or_b32_e32 v36, v3, v38
	v_or_b32_e32 v38, v3, v40
	v_or_b32_e32 v40, v3, v42
	v_or_b32_e32 v42, v3, v46
	v_lshl_add_u64 v[46:47], v[4:5], 2, s[68:69]
	v_or_b32_e32 v4, v16, v63
	s_add_i32 s43, s30, 24
	v_or_b32_e32 v58, s41, v2
	v_add_lshl_u32 v65, v56, s3, 9
	v_lshl_add_u64 v[22:23], v[22:23], 2, s[68:69]
	global_load_dword v63, v[44:45], off nt
	global_load_dword v69, v[20:21], off nt
	global_load_dword v70, v[46:47], off nt
	global_load_dword v71, v[22:23], off nt
	v_lshl_add_u64 v[20:21], v[4:5], 2, s[68:69]
	v_or_b32_e32 v4, v16, v64
	v_mov_b32_e32 v33, v5
	v_mov_b32_e32 v35, v5
	s_add_i32 s30, s30, 28
	v_or_b32_e32 v60, s43, v2
	v_add_lshl_u32 v66, v58, s3, 9
	v_lshl_add_u64 v[22:23], v[4:5], 2, s[68:69]
	v_or_b32_e32 v4, v16, v65
	v_or_b32_e32 v62, s30, v2
	v_add_lshl_u32 v67, v60, s3, 9
	v_lshl_add_u64 v[32:33], v[32:33], 2, s[68:69]
	v_lshl_add_u64 v[34:35], v[34:35], 2, s[68:69]
	global_load_dword v64, v[20:21], off nt
	global_load_dword v65, v[32:33], off nt
	global_load_dword v72, v[22:23], off nt
	global_load_dword v73, v[34:35], off nt
	v_lshl_add_u64 v[20:21], v[4:5], 2, s[68:69]
	v_or_b32_e32 v4, v16, v66
	s_waitcnt lgkmcnt(0)
	v_mov_b32_e32 v37, v5
	v_mov_b32_e32 v39, v5
	v_add_lshl_u32 v68, v62, s3, 9
	v_lshl_add_u64 v[22:23], v[4:5], 2, s[68:69]
	v_or_b32_e32 v4, v16, v67
	v_mov_b32_e32 v41, v5
	v_mov_b32_e32 v43, v5
	v_lshl_add_u64 v[36:37], v[36:37], 2, s[68:69]
	v_lshl_add_u64 v[38:39], v[38:39], 2, s[68:69]
	global_load_dword v66, v[20:21], off nt
	global_load_dword v67, v[36:37], off nt
	global_load_dword v74, v[22:23], off nt
	global_load_dword v75, v[38:39], off nt
	v_lshl_add_u64 v[20:21], v[4:5], 2, s[68:69]
	v_or_b32_e32 v4, v16, v68
	v_lshl_add_u64 v[40:41], v[40:41], 2, s[68:69]
	v_lshl_add_u64 v[42:43], v[42:43], 2, s[68:69]
	v_lshl_add_u64 v[22:23], v[4:5], 2, s[68:69]
	global_load_dword v4, v[20:21], off nt
	global_load_dword v68, v[40:41], off nt
	global_load_dword v76, v[22:23], off nt
	global_load_dword v77, v[42:43], off nt
	s_add_i32 s27, s27, 16
	s_add_i32 s26, s26, 16
	s_add_i32 s28, s28, -16
	v_mad_u64_u32 v[20:21], s[30:31], v48, s1, v[6:7]
	s_cmp_lg_u32 s28, 0
	v_mad_u64_u32 v[22:23], s[30:31], v17, s1, v[6:7]
	v_mad_u64_u32 v[32:33], s[30:31], v50, s1, v[6:7]
	v_mad_u64_u32 v[34:35], s[30:31], v49, s1, v[6:7]
	v_mad_u64_u32 v[36:37], s[30:31], v52, s1, v[6:7]
	v_mad_u64_u32 v[38:39], s[30:31], v51, s1, v[6:7]
	v_mad_u64_u32 v[40:41], s[30:31], v54, s1, v[6:7]
	v_mad_u64_u32 v[42:43], s[30:31], v53, s1, v[6:7]
	v_mad_u64_u32 v[44:45], s[30:31], v56, s1, v[6:7]
	v_mad_u64_u32 v[46:47], s[30:31], v55, s1, v[6:7]
	v_mad_u64_u32 v[48:49], s[30:31], v58, s1, v[6:7]
	v_mad_u64_u32 v[50:51], s[30:31], v57, s1, v[6:7]
	v_mad_u64_u32 v[52:53], s[30:31], v60, s1, v[6:7]
	v_mad_u64_u32 v[54:55], s[30:31], v59, s1, v[6:7]
	v_mad_u64_u32 v[56:57], s[30:31], v62, s1, v[6:7]
	v_mad_u64_u32 v[58:59], s[30:31], v61, s1, v[6:7]
	s_waitcnt vmcnt(15)
	ds_write_b32 v20, v63 offset:49152
	s_waitcnt vmcnt(14)
	ds_write_b32 v22, v69 offset:49152
	s_waitcnt vmcnt(13)
	ds_write_b32 v32, v70 offset:49152
	s_waitcnt vmcnt(12)
	ds_write_b32 v34, v71 offset:49152
	s_waitcnt vmcnt(11)
	ds_write_b32 v36, v64 offset:49152
	s_waitcnt vmcnt(10)
	ds_write_b32 v38, v65 offset:49152
	s_waitcnt vmcnt(9)
	ds_write_b32 v40, v72 offset:49152
	s_waitcnt vmcnt(8)
	ds_write_b32 v42, v73 offset:49152
	s_waitcnt vmcnt(7)
	ds_write_b32 v44, v66 offset:49152
	s_waitcnt vmcnt(6)
	ds_write_b32 v46, v67 offset:49152
	s_waitcnt vmcnt(5)
	ds_write_b32 v48, v74 offset:49152
	s_waitcnt vmcnt(4)
	ds_write_b32 v50, v75 offset:49152
	s_waitcnt vmcnt(3)
	ds_write_b32 v52, v4 offset:49152
	s_waitcnt vmcnt(2)
	ds_write_b32 v54, v68 offset:49152
	s_waitcnt vmcnt(1)
	ds_write_b32 v56, v76 offset:49152
	s_waitcnt vmcnt(0)
	ds_write_b32 v58, v77 offset:49152
	s_cbranch_scc1 .LBB0_58
; #define LAS __attribute__((address_space(3)))
; __device__ __forceinline__ unsigned pk2(float lo, float hi) { const f32x2c_t v = {lo, hi}; return __builtin_bit_cast(unsigned, __builtin_convertvector(v, bf16x2c_t)); }
; template <int MODE>
; __device__ __forceinline__ void transpose_item(const float* W, int K, int N, bf16_t* WT, const float* gain, LAS float* scr, int item, int lane) {
;     ...
;     const int c = lane & 7;
; #pragma unroll
;     for (int j = 0; j < 4; ++j) { const int n = (lane >> 3) + 8 * j; const LAS float* s = scr + (8 * c) * 33 + n;
;         u32x4 o; o.x = pk2(s[0 * 33], s[1 * 33]); o.y = pk2(s[2 * 33], s[3 * 33]); o.z = pk2(s[4 * 33], s[5 * 33]); o.w = pk2(s[6 * 33], s[7 * 33]);
;         const int drow = inproj_row(n0 + n);
;         *(u32x4*)(WT + (size_t)drow * K + k0 + 8 * c) = o; }
	v_or_b32_e32 v3, v7, v24
	v_lshlrev_b32_e32 v3, 2, v3
	v_lshlrev_b32_e32 v4, 4, v18
	v_and_b32_e32 v48, 0x60, v4
	v_bitop3_b32 v4, v7, s17, v24 bitop3:0xc8
	v_and_b32_e32 v3, 0x90, v3
	v_or3_b32 v3, v4, v3, v48
	ds_read2_b32 v[16:17], v31 offset0:33 offset1:41
	ds_read2_b32 v[32:33], v31 offset1:8
	ds_read2_b32 v[34:35], v31 offset0:66 offset1:74
	ds_read2_b32 v[36:37], v31 offset0:99 offset1:107
	ds_read2_b32 v[38:39], v31 offset0:132 offset1:140
	ds_read2_b32 v[40:41], v31 offset0:165 offset1:173
	ds_read2_b32 v[42:43], v31 offset0:198 offset1:206
	ds_read2_b32 v[44:45], v31 offset0:231 offset1:239
	v_lshlrev_b32_e32 v4, 10, v3
	v_or_b32_e32 v3, v7, v25
	v_lshlrev_b32_e32 v3, 2, v3
	v_lshl_add_u64 v[46:47], v[10:11], 0, v[4:5]
	v_bitop3_b32 v4, v7, s17, v25 bitop3:0xc8
	v_and_b32_e32 v3, 0x90, v3
	v_or3_b32 v3, v4, v3, v48
	v_lshlrev_b32_e32 v4, 10, v3
	v_or_b32_e32 v3, v7, v29
	s_waitcnt lgkmcnt(6)
	v_cvt_pk_bf16_f32 v20, v32, v16
	s_waitcnt lgkmcnt(4)
	v_cvt_pk_bf16_f32 v21, v34, v36
	s_waitcnt lgkmcnt(2)
	v_cvt_pk_bf16_f32 v22, v38, v40
	s_waitcnt lgkmcnt(0)
	v_cvt_pk_bf16_f32 v23, v42, v44
	v_lshlrev_b32_e32 v3, 2, v3
	global_store_dwordx4 v[46:47], v[20:23], off
	v_and_b32_e32 v3, 0x90, v3
	s_nop 0
	v_cvt_pk_bf16_f32 v20, v33, v17
	v_lshl_add_u64 v[16:17], v[10:11], 0, v[4:5]
	v_bitop3_b32 v4, v7, s17, v29 bitop3:0xc8
	v_cvt_pk_bf16_f32 v21, v35, v37
	v_cvt_pk_bf16_f32 v22, v39, v41
	v_cvt_pk_bf16_f32 v23, v43, v45
	ds_read2_b32 v[32:33], v31 offset0:49 offset1:57
	ds_read2_b32 v[34:35], v31 offset0:16 offset1:24
	ds_read2_b32 v[36:37], v31 offset0:82 offset1:90
	ds_read2_b32 v[38:39], v31 offset0:115 offset1:123
	ds_read2_b32 v[40:41], v31 offset0:148 offset1:156
	ds_read2_b32 v[42:43], v31 offset0:181 offset1:189
	ds_read2_b32 v[44:45], v31 offset0:214 offset1:222
	ds_read2_b32 v[46:47], v31 offset0:247 offset1:255
	v_or3_b32 v3, v4, v3, v48
	v_add_co_u32_e32 v16, vcc, s18, v16
	v_lshlrev_b32_e32 v4, 10, v3
	v_or_b32_e32 v3, v7, v30
	v_addc_co_u32_e32 v17, vcc, 0, v17, vcc
	v_lshlrev_b32_e32 v3, 2, v3
	global_store_dwordx4 v[16:17], v[20:23], off
	v_lshl_add_u64 v[16:17], v[10:11], 0, v[4:5]
	v_bitop3_b32 v4, v7, s17, v30 bitop3:0xc8
	v_and_b32_e32 v3, 0x90, v3
	v_add_co_u32_e32 v16, vcc, s19, v16
	v_or3_b32 v3, v4, v3, v48
	s_waitcnt lgkmcnt(6)
	v_cvt_pk_bf16_f32 v20, v34, v32
	s_waitcnt lgkmcnt(4)
	v_cvt_pk_bf16_f32 v21, v36, v38
	s_waitcnt lgkmcnt(2)
	v_cvt_pk_bf16_f32 v22, v40, v42
	s_waitcnt lgkmcnt(0)
	v_cvt_pk_bf16_f32 v23, v44, v46
	v_addc_co_u32_e32 v17, vcc, 0, v17, vcc
	v_lshlrev_b32_e32 v4, 10, v3
	global_store_dwordx4 v[16:17], v[20:23], off
	v_lshl_add_u64 v[16:17], v[10:11], 0, v[4:5]
	v_add_co_u32_e32 v16, vcc, 0x3000, v16
	v_cvt_pk_bf16_f32 v20, v35, v33
	v_cvt_pk_bf16_f32 v21, v37, v39
	v_cvt_pk_bf16_f32 v22, v41, v43
	v_cvt_pk_bf16_f32 v23, v45, v47
	v_addc_co_u32_e32 v17, vcc, 0, v17, vcc
	global_store_dwordx4 v[16:17], v[20:23], off

; template <int MODE>
; __device__ __forceinline__ void transpose_item(const float* W, int K, int N, bf16_t* WT, const float* gain, LAS float* scr, int item, int lane) {
;     const int nblk = N / 32, kb = item / nblk, nb = item % nblk, k0 = 64 * kb, n0 = 32 * nb;
; #pragma unroll 8
;     for (int i = 0; i < 32; ++i) { const int kk = 2 * i + (lane >> 5); float w = W[(size_t)(k0 + kk) * N + n0 + (lane & 31)]; if (MODE == 0) w *= gain[k0 + kk]; scr[kk * 33 + (lane & 31)] = w; }
.LBB0_62:
	s_lshl_b32 s29, s26, 1
	s_lshl_b32 s30, s27, 1
	v_or_b32_e32 v21, s29, v1
	v_or_b32_e32 v50, s30, v2
	s_add_i32 s33, s30, 4
	s_add_i32 s31, s29, 4
	s_add_i32 s34, s29, 8
	s_add_i32 s35, s30, 8
	s_add_i32 s36, s29, 12
	s_add_i32 s38, s29, 16
	s_add_i32 s40, s29, 20
	s_add_i32 s42, s29, 24
	s_add_i32 s29, s29, 28
	v_add_lshl_u32 v4, v21, v3, 10
	v_add_lshl_u32 v32, v50, v16, 10
	v_or_b32_e32 v52, s33, v2
	s_add_i32 s37, s30, 12
	v_or_b32_e32 v51, s31, v1
	v_or_b32_e32 v53, s34, v1
	v_or_b32_e32 v54, s35, v2
	v_or_b32_e32 v55, s36, v1
	v_or_b32_e32 v57, s38, v1
	v_or_b32_e32 v59, s40, v1
	v_or_b32_e32 v61, s42, v1
	v_or_b32_e32 v63, s29, v1
	v_or_b32_e32 v22, v7, v4
	v_or_b32_e32 v4, v20, v32
	v_add_lshl_u32 v34, v52, v16, 10
	v_mov_b32_e32 v23, v5
	s_add_i32 s39, s30, 16
	v_or_b32_e32 v56, s37, v2
	v_add_lshl_u32 v32, v51, v3, 10
	v_add_lshl_u32 v36, v53, v3, 10
	v_add_lshl_u32 v65, v54, v16, 10
	v_add_lshl_u32 v38, v55, v3, 10
	v_add_lshl_u32 v40, v57, v3, 10
	v_add_lshl_u32 v42, v59, v3, 10
	v_add_lshl_u32 v44, v61, v3, 10
	v_add_lshl_u32 v48, v63, v3, 10
	v_lshl_add_u64 v[46:47], v[4:5], 2, s[82:83]
	v_or_b32_e32 v4, v20, v34
	v_mov_b32_e32 v33, v5
	s_add_i32 s41, s30, 20
	v_or_b32_e32 v58, s39, v2
	v_add_lshl_u32 v66, v56, v16, 10
	v_lshl_add_u64 v[22:23], v[22:23], 2, s[82:83]
	v_or_b32_e32 v32, v7, v32
	v_or_b32_e32 v34, v7, v36
	v_or_b32_e32 v36, v7, v38
	v_or_b32_e32 v38, v7, v40
	v_or_b32_e32 v40, v7, v42
	v_or_b32_e32 v42, v7, v44
	v_or_b32_e32 v44, v7, v48
	v_lshl_add_u64 v[48:49], v[4:5], 2, s[82:83]
	v_or_b32_e32 v4, v20, v65
	s_add_i32 s43, s30, 24
	v_or_b32_e32 v60, s41, v2
	v_add_lshl_u32 v67, v58, v16, 10
	v_lshl_add_u64 v[32:33], v[32:33], 2, s[82:83]
	global_load_dword v65, v[46:47], off nt
	global_load_dword v71, v[22:23], off nt
	global_load_dword v72, v[48:49], off nt
	global_load_dword v73, v[32:33], off nt
	v_lshl_add_u64 v[22:23], v[4:5], 2, s[82:83]
	v_or_b32_e32 v4, v20, v66
	v_mov_b32_e32 v35, v5
	s_waitcnt lgkmcnt(0)
	v_mov_b32_e32 v37, v5
	s_add_i32 s30, s30, 28
	v_or_b32_e32 v62, s43, v2
	v_add_lshl_u32 v68, v60, v16, 10
	v_lshl_add_u64 v[32:33], v[4:5], 2, s[82:83]
	v_or_b32_e32 v4, v20, v67
	v_or_b32_e32 v64, s30, v2
	v_add_lshl_u32 v69, v62, v16, 10
	v_lshl_add_u64 v[34:35], v[34:35], 2, s[82:83]
	v_lshl_add_u64 v[36:37], v[36:37], 2, s[82:83]
	global_load_dword v66, v[22:23], off nt
	global_load_dword v67, v[34:35], off nt
	global_load_dword v74, v[32:33], off nt
	global_load_dword v75, v[36:37], off nt
	v_lshl_add_u64 v[22:23], v[4:5], 2, s[82:83]
	v_or_b32_e32 v4, v20, v68
	v_mov_b32_e32 v39, v5
	v_mov_b32_e32 v41, v5
	v_add_lshl_u32 v70, v64, v16, 10
	v_lshl_add_u64 v[32:33], v[4:5], 2, s[82:83]
	v_or_b32_e32 v4, v20, v69
	v_mov_b32_e32 v43, v5
	v_mov_b32_e32 v45, v5
	v_lshl_add_u64 v[38:39], v[38:39], 2, s[82:83]
	v_lshl_add_u64 v[40:41], v[40:41], 2, s[82:83]
	global_load_dword v68, v[22:23], off nt
	global_load_dword v69, v[38:39], off nt
	global_load_dword v76, v[32:33], off nt
	global_load_dword v77, v[40:41], off nt
	v_lshl_add_u64 v[22:23], v[4:5], 2, s[82:83]
	v_or_b32_e32 v4, v20, v70
	v_lshl_add_u64 v[42:43], v[42:43], 2, s[82:83]
	v_lshl_add_u64 v[44:45], v[44:45], 2, s[82:83]
	v_lshl_add_u64 v[32:33], v[4:5], 2, s[82:83]
	global_load_dword v4, v[22:23], off nt
	global_load_dword v70, v[42:43], off nt
	global_load_dword v78, v[32:33], off nt
	global_load_dword v79, v[44:45], off nt
	s_add_i32 s27, s27, 16
	s_add_i32 s26, s26, 16
	s_add_i32 s28, s28, -16
	v_mad_u64_u32 v[22:23], s[30:31], v50, s1, v[6:7]
	s_cmp_lg_u32 s28, 0
	v_mad_u64_u32 v[32:33], s[30:31], v21, s1, v[6:7]
	v_mad_u64_u32 v[34:35], s[30:31], v52, s1, v[6:7]
	v_mad_u64_u32 v[36:37], s[30:31], v51, s1, v[6:7]
	v_mad_u64_u32 v[38:39], s[30:31], v54, s1, v[6:7]
	v_mad_u64_u32 v[40:41], s[30:31], v53, s1, v[6:7]
	v_mad_u64_u32 v[42:43], s[30:31], v56, s1, v[6:7]
	v_mad_u64_u32 v[44:45], s[30:31], v55, s1, v[6:7]
	v_mad_u64_u32 v[46:47], s[30:31], v58, s1, v[6:7]
	v_mad_u64_u32 v[48:49], s[30:31], v57, s1, v[6:7]
	v_mad_u64_u32 v[50:51], s[30:31], v60, s1, v[6:7]
	v_mad_u64_u32 v[52:53], s[30:31], v59, s1, v[6:7]
	v_mad_u64_u32 v[54:55], s[30:31], v62, s1, v[6:7]
	v_mad_u64_u32 v[56:57], s[30:31], v61, s1, v[6:7]
	v_mad_u64_u32 v[58:59], s[30:31], v64, s1, v[6:7]
	v_mad_u64_u32 v[60:61], s[30:31], v63, s1, v[6:7]
	s_waitcnt vmcnt(15)
	ds_write_b32 v22, v65 offset:49152
	s_waitcnt vmcnt(14)
	ds_write_b32 v32, v71 offset:49152
	s_waitcnt vmcnt(13)
	ds_write_b32 v34, v72 offset:49152
	s_waitcnt vmcnt(12)
	ds_write_b32 v36, v73 offset:49152
	s_waitcnt vmcnt(11)
	ds_write_b32 v38, v66 offset:49152
	s_waitcnt vmcnt(10)
	ds_write_b32 v40, v67 offset:49152
	s_waitcnt vmcnt(9)
	ds_write_b32 v42, v74 offset:49152
	s_waitcnt vmcnt(8)
	ds_write_b32 v44, v75 offset:49152
	s_waitcnt vmcnt(7)
	ds_write_b32 v46, v68 offset:49152
	s_waitcnt vmcnt(6)
	ds_write_b32 v48, v69 offset:49152
	s_waitcnt vmcnt(5)
	ds_write_b32 v50, v76 offset:49152
	s_waitcnt vmcnt(4)
	ds_write_b32 v52, v77 offset:49152
	s_waitcnt vmcnt(3)
	ds_write_b32 v54, v4 offset:49152
	s_waitcnt vmcnt(2)
	ds_write_b32 v56, v70 offset:49152
	s_waitcnt vmcnt(1)
	ds_write_b32 v58, v78 offset:49152
	s_waitcnt vmcnt(0)
	ds_write_b32 v60, v79 offset:49152
	s_cbranch_scc1 .LBB0_62
; #define LAS __attribute__((address_space(3)))
; __device__ __forceinline__ unsigned pk2(float lo, float hi) { const f32x2c_t v = {lo, hi}; return __builtin_bit_cast(unsigned, __builtin_convertvector(v, bf16x2c_t)); }
; template <int MODE>
; __device__ __forceinline__ void transpose_item(const float* W, int K, int N, bf16_t* WT, const float* gain, LAS float* scr, int item, int lane) {
;     ...
;     const int c = lane & 7;
; #pragma unroll
;     for (int j = 0; j < 4; ++j) { const int n = (lane >> 3) + 8 * j; const LAS float* s = scr + (8 * c) * 33 + n;
;         u32x4 o; o.x = pk2(s[0 * 33], s[1 * 33]); o.y = pk2(s[2 * 33], s[3 * 33]); o.z = pk2(s[4 * 33], s[5 * 33]); o.w = pk2(s[6 * 33], s[7 * 33]);
;         const int drow = inproj_row(n0 + n);
;         *(u32x4*)(WT + (size_t)drow * K + k0 + 8 * c) = o; }
	v_lshlrev_b32_e32 v4, 1, v16
	v_or_b32_e32 v3, v17, v24
	v_lshl_add_u64 v[48:49], v[12:13], 0, v[4:5]
	v_lshlrev_b32_e32 v3, 2, v3
	v_lshlrev_b32_e32 v4, 4, v18
	v_and_b32_e32 v7, 0x60, v4
	v_bitop3_b32 v4, v17, s21, v24 bitop3:0xc8
	v_and_b32_e32 v3, 0x90, v3
	v_or3_b32 v3, v4, v3, v7
	ds_read2_b32 v[32:33], v31 offset0:33 offset1:41
	ds_read2_b32 v[34:35], v31 offset1:8
	ds_read2_b32 v[36:37], v31 offset0:66 offset1:74
	ds_read2_b32 v[38:39], v31 offset0:99 offset1:107
	ds_read2_b32 v[40:41], v31 offset0:132 offset1:140
	ds_read2_b32 v[42:43], v31 offset0:165 offset1:173
	ds_read2_b32 v[44:45], v31 offset0:198 offset1:206
	ds_read2_b32 v[46:47], v31 offset0:231 offset1:239
	v_lshlrev_b32_e32 v4, 11, v3
	v_or_b32_e32 v3, v17, v25
	v_lshlrev_b32_e32 v3, 2, v3
	v_lshl_add_u64 v[50:51], v[48:49], 0, v[4:5]
	v_bitop3_b32 v4, v17, s21, v25 bitop3:0xc8
	v_and_b32_e32 v3, 0x90, v3
	v_or3_b32 v3, v4, v3, v7
	v_lshlrev_b32_e32 v4, 11, v3
	v_or_b32_e32 v3, v17, v29
	s_waitcnt lgkmcnt(6)
	v_cvt_pk_bf16_f32 v20, v34, v32
	s_waitcnt lgkmcnt(4)
	v_cvt_pk_bf16_f32 v21, v36, v38
	s_waitcnt lgkmcnt(2)
	v_cvt_pk_bf16_f32 v22, v40, v42
	s_waitcnt lgkmcnt(0)
	v_cvt_pk_bf16_f32 v23, v44, v46
	v_lshlrev_b32_e32 v3, 2, v3
	global_store_dwordx4 v[50:51], v[20:23], off
	v_and_b32_e32 v3, 0x90, v3
	s_nop 0
	v_cvt_pk_bf16_f32 v20, v35, v33
	v_lshl_add_u64 v[32:33], v[48:49], 0, v[4:5]
	v_bitop3_b32 v4, v17, s21, v29 bitop3:0xc8
	v_or3_b32 v3, v4, v3, v7
	v_add_co_u32_e32 v32, vcc, s19, v32
	v_lshlrev_b32_e32 v4, 11, v3
	v_or_b32_e32 v3, v17, v30
	v_cvt_pk_bf16_f32 v21, v37, v39
	v_cvt_pk_bf16_f32 v22, v41, v43
	v_cvt_pk_bf16_f32 v23, v45, v47
	v_addc_co_u32_e32 v33, vcc, 0, v33, vcc
	ds_read2_b32 v[34:35], v31 offset0:49 offset1:57
	ds_read2_b32 v[36:37], v31 offset0:16 offset1:24
	ds_read2_b32 v[38:39], v31 offset0:82 offset1:90
	ds_read2_b32 v[40:41], v31 offset0:115 offset1:123
	ds_read2_b32 v[42:43], v31 offset0:148 offset1:156
	ds_read2_b32 v[44:45], v31 offset0:181 offset1:189
	ds_read2_b32 v[46:47], v31 offset0:214 offset1:222
	ds_read2_b32 v[50:51], v31 offset0:247 offset1:255
	v_lshlrev_b32_e32 v3, 2, v3
	global_store_dwordx4 v[32:33], v[20:23], off
	v_lshl_add_u64 v[32:33], v[48:49], 0, v[4:5]
	v_bitop3_b32 v4, v17, s21, v30 bitop3:0xc8
	v_and_b32_e32 v3, 0x90, v3
	v_or3_b32 v3, v4, v3, v7
	v_add_co_u32_e32 v32, vcc, s22, v32
	v_lshlrev_b32_e32 v4, 11, v3
	s_nop 0
	v_addc_co_u32_e32 v33, vcc, 0, v33, vcc
	v_lshl_add_u64 v[16:17], v[48:49], 0, v[4:5]
	s_waitcnt lgkmcnt(6)
	v_cvt_pk_bf16_f32 v20, v36, v34
	s_waitcnt lgkmcnt(4)
	v_cvt_pk_bf16_f32 v21, v38, v40
	s_waitcnt lgkmcnt(2)
	v_cvt_pk_bf16_f32 v22, v42, v44
	s_waitcnt lgkmcnt(0)
	v_cvt_pk_bf16_f32 v23, v46, v50
	v_add_co_u32_e32 v16, vcc, 0x6000, v16
	global_store_dwordx4 v[32:33], v[20:23], off
	s_nop 0
	v_addc_co_u32_e32 v17, vcc, 0, v17, vcc
	v_cvt_pk_bf16_f32 v20, v37, v35
	v_cvt_pk_bf16_f32 v21, v39, v41
	v_cvt_pk_bf16_f32 v22, v43, v45
	v_cvt_pk_bf16_f32 v23, v47, v51
	global_store_dwordx4 v[16:17], v[20:23], off

; template <int MODE>
; __device__ __forceinline__ void transpose_item(const float* W, int K, int N, bf16_t* WT, const float* gain, LAS float* scr, int item, int lane) {
;     const int nblk = N / 32, kb = item / nblk, nb = item % nblk, k0 = 64 * kb, n0 = 32 * nb;
; #pragma unroll 8
;     for (int i = 0; i < 32; ++i) { const int kk = 2 * i + (lane >> 5); float w = W[(size_t)(k0 + kk) * N + n0 + (lane & 31)]; if (MODE == 0) w *= gain[k0 + kk]; scr[kk * 33 + (lane & 31)] = w; }
.LBB0_67:
	s_lshl_b32 s27, s10, 1
	s_lshl_b32 s28, s11, 1
	s_add_i32 s29, s27, 4
	s_add_i32 s30, s28, 4
	s_add_i32 s31, s27, 8
	s_add_i32 s33, s28, 8
	s_add_i32 s34, s27, 12
	s_add_i32 s35, s28, 12
	s_add_i32 s36, s27, 16
	v_or_b32_e32 v32, s27, v3
	v_or_b32_e32 v34, s28, v4
	s_add_i32 s37, s28, 16
	s_add_i32 s40, s27, 20
	s_add_i32 s41, s28, 20
	s_add_i32 s42, s27, 24
	s_add_i32 s43, s28, 24
	s_add_i32 s44, s27, 28
	s_add_i32 s45, s28, 28
	v_or_b32_e32 v40, s29, v3
	v_or_b32_e32 v42, s30, v4
	v_or_b32_e32 v44, s31, v3
	v_or_b32_e32 v46, s33, v4
	v_or_b32_e32 v48, s34, v3
	v_or_b32_e32 v50, s35, v4
	v_or_b32_e32 v52, s36, v3
	v_ashrrev_i32_e32 v33, 31, v32
	v_ashrrev_i32_e32 v35, 31, v34
	s_waitcnt lgkmcnt(0)
	v_mad_i64_i32 v[36:37], s[38:39], v34, s20, v[22:23]
	v_mad_i64_i32 v[38:39], s[38:39], v32, s20, v[22:23]
	v_or_b32_e32 v54, s37, v4
	v_or_b32_e32 v56, s40, v3
	v_or_b32_e32 v58, s41, v4
	v_or_b32_e32 v60, s42, v3
	v_or_b32_e32 v62, s43, v4
	v_or_b32_e32 v64, s44, v3
	v_or_b32_e32 v66, s45, v4
	v_ashrrev_i32_e32 v41, 31, v40
	v_ashrrev_i32_e32 v43, 31, v42
	v_ashrrev_i32_e32 v45, 31, v44
	v_ashrrev_i32_e32 v47, 31, v46
	v_ashrrev_i32_e32 v49, 31, v48
	v_ashrrev_i32_e32 v51, 31, v50
	v_ashrrev_i32_e32 v53, 31, v52
	global_load_dword v36, v[36:37], off nt
	s_nop 0
	global_load_dword v37, v[38:39], off nt
	v_lshl_add_u64 v[34:35], v[34:35], 2, s[78:79]
	v_lshl_add_u64 v[32:33], v[32:33], 2, s[78:79]
	v_mad_i64_i32 v[38:39], s[38:39], v42, s20, v[22:23]
	v_mad_i64_i32 v[68:69], s[38:39], v40, s20, v[22:23]
	v_mad_i64_i32 v[70:71], s[38:39], v46, s20, v[22:23]
	v_mad_i64_i32 v[72:73], s[38:39], v44, s20, v[22:23]
	v_mad_i64_i32 v[74:75], s[38:39], v50, s20, v[22:23]
	v_mad_i64_i32 v[76:77], s[38:39], v48, s20, v[22:23]
	v_ashrrev_i32_e32 v55, 31, v54
	v_mad_i64_i32 v[80:81], s[38:39], v52, s20, v[22:23]
	v_ashrrev_i32_e32 v57, 31, v56
	v_ashrrev_i32_e32 v59, 31, v58
	v_ashrrev_i32_e32 v61, 31, v60
	v_ashrrev_i32_e32 v63, 31, v62
	v_ashrrev_i32_e32 v65, 31, v64
	v_ashrrev_i32_e32 v67, 31, v66
	v_mad_i64_i32 v[90:91], s[38:39], v66, s20, v[22:23]
	v_lshl_add_u64 v[42:43], v[42:43], 2, s[78:79]
	v_lshl_add_u64 v[40:41], v[40:41], 2, s[78:79]
	v_lshl_add_u64 v[46:47], v[46:47], 2, s[78:79]
	v_lshl_add_u64 v[44:45], v[44:45], 2, s[78:79]
	v_lshl_add_u64 v[50:51], v[50:51], 2, s[78:79]
	v_lshl_add_u64 v[48:49], v[48:49], 2, s[78:79]
	v_lshl_add_u64 v[52:53], v[52:53], 2, s[78:79]
	v_mad_i64_i32 v[78:79], s[38:39], v54, s20, v[22:23]
	v_mad_i64_i32 v[82:83], s[38:39], v58, s20, v[22:23]
	v_mad_i64_i32 v[84:85], s[38:39], v56, s20, v[22:23]
	v_mad_i64_i32 v[86:87], s[38:39], v62, s20, v[22:23]
	v_mad_i64_i32 v[88:89], s[38:39], v60, s20, v[22:23]
	v_mad_i64_i32 v[92:93], s[38:39], v64, s20, v[22:23]
	global_load_dword v34, v[34:35], off nt
	s_nop 0
	global_load_dword v35, v[32:33], off nt
	s_nop 0
	global_load_dword v32, v[38:39], off nt
	global_load_dword v33, v[68:69], off nt
	s_nop 0
	global_load_dword v38, v[70:71], off nt
	global_load_dword v39, v[72:73], off nt
	global_load_dword v68, v[74:75], off nt
	global_load_dword v69, v[76:77], off nt
	s_nop 0
	global_load_dword v70, v[78:79], off nt
	global_load_dword v71, v[80:81], off nt
	global_load_dword v72, v[82:83], off nt
	global_load_dword v73, v[84:85], off nt
	global_load_dword v74, v[86:87], off nt
	global_load_dword v75, v[88:89], off nt
	v_lshl_add_u64 v[54:55], v[54:55], 2, s[78:79]
	v_lshl_add_u64 v[58:59], v[58:59], 2, s[78:79]
	v_lshl_add_u64 v[56:57], v[56:57], 2, s[78:79]
	v_lshl_add_u64 v[62:63], v[62:63], 2, s[78:79]
	v_lshl_add_u64 v[60:61], v[60:61], 2, s[78:79]
	global_load_dword v76, v[90:91], off nt
	global_load_dword v77, v[92:93], off nt
	v_lshl_add_u64 v[66:67], v[66:67], 2, s[78:79]
	v_lshl_add_u64 v[64:65], v[64:65], 2, s[78:79]
	global_load_dword v42, v[42:43], off nt
	s_nop 0
	global_load_dword v43, v[40:41], off nt
	s_nop 0
	global_load_dword v40, v[46:47], off nt
	global_load_dword v41, v[44:45], off nt
	s_nop 0
	global_load_dword v44, v[50:51], off nt
	global_load_dword v45, v[48:49], off nt
	global_load_dword v46, v[54:55], off nt
	global_load_dword v47, v[52:53], off nt
	s_nop 0
	global_load_dword v48, v[58:59], off nt
	global_load_dword v49, v[56:57], off nt
	global_load_dword v50, v[62:63], off nt
	global_load_dword v51, v[60:61], off nt
	global_load_dword v52, v[66:67], off nt
	global_load_dword v53, v[64:65], off nt
	v_or_b32_e32 v7, s27, v1
	v_or_b32_e32 v17, s28, v2
	s_add_i32 s11, s11, 16
	s_add_i32 s10, s10, 16
	s_add_i32 s26, s26, -16
	v_mad_u64_u32 v[54:55], s[38:39], v17, s1, v[6:7]
	v_mad_u64_u32 v[56:57], s[38:39], v7, s1, v[6:7]
	v_or_b32_e32 v7, s29, v1
	v_or_b32_e32 v17, s30, v2
	v_or_b32_e32 v21, s31, v1
	v_or_b32_e32 v55, s33, v2
	v_or_b32_e32 v57, s34, v1
	v_or_b32_e32 v66, s35, v2
	v_or_b32_e32 v82, s36, v1
	v_or_b32_e32 v80, s37, v2
	v_or_b32_e32 v86, s40, v1
	v_or_b32_e32 v84, s41, v2
	v_or_b32_e32 v90, s42, v1
	v_or_b32_e32 v88, s43, v2
	v_or_b32_e32 v94, s44, v1
	v_or_b32_e32 v92, s45, v2
	s_cmp_lg_u32 s26, 0
	v_mad_u64_u32 v[58:59], s[28:29], v17, s1, v[6:7]
	v_mad_u64_u32 v[60:61], s[28:29], v7, s1, v[6:7]
	v_mad_u64_u32 v[62:63], s[28:29], v55, s1, v[6:7]
	v_mad_u64_u32 v[64:65], s[28:29], v21, s1, v[6:7]
	v_mad_u64_u32 v[66:67], s[28:29], v66, s1, v[6:7]
	v_mad_u64_u32 v[78:79], s[28:29], v57, s1, v[6:7]
	v_mad_u64_u32 v[80:81], s[28:29], v80, s1, v[6:7]
	v_mad_u64_u32 v[82:83], s[28:29], v82, s1, v[6:7]
	v_mad_u64_u32 v[84:85], s[28:29], v84, s1, v[6:7]
	v_mad_u64_u32 v[86:87], s[28:29], v86, s1, v[6:7]
	v_mad_u64_u32 v[88:89], s[28:29], v88, s1, v[6:7]
	v_mad_u64_u32 v[90:91], s[28:29], v90, s1, v[6:7]
	v_mad_u64_u32 v[92:93], s[28:29], v92, s1, v[6:7]
	v_mad_u64_u32 v[94:95], s[28:29], v94, s1, v[6:7]
	s_waitcnt vmcnt(28)
	v_pk_mul_f32 v[34:35], v[36:37], v[34:35]
	ds_write_b32 v54, v34 offset:49152
	ds_write_b32 v56, v35 offset:49152
	s_waitcnt vmcnt(12)
	v_pk_mul_f32 v[32:33], v[32:33], v[42:43]
	s_waitcnt vmcnt(10)
	v_pk_mul_f32 v[34:35], v[38:39], v[40:41]
	s_waitcnt vmcnt(8)
	v_pk_mul_f32 v[36:37], v[68:69], v[44:45]
	s_waitcnt vmcnt(6)
	v_pk_mul_f32 v[38:39], v[70:71], v[46:47]
	s_waitcnt vmcnt(4)
	v_pk_mul_f32 v[40:41], v[72:73], v[48:49]
	s_waitcnt vmcnt(2)
	v_pk_mul_f32 v[42:43], v[74:75], v[50:51]
	s_waitcnt vmcnt(0)
	v_pk_mul_f32 v[44:45], v[76:77], v[52:53]
	ds_write_b32 v58, v32 offset:49152
	ds_write_b32 v60, v33 offset:49152
	ds_write_b32 v62, v34 offset:49152
	ds_write_b32 v64, v35 offset:49152
	ds_write_b32 v66, v36 offset:49152
	ds_write_b32 v78, v37 offset:49152
	ds_write_b32 v80, v38 offset:49152
	ds_write_b32 v82, v39 offset:49152
	ds_write_b32 v84, v40 offset:49152
	ds_write_b32 v86, v41 offset:49152
	ds_write_b32 v88, v42 offset:49152
	ds_write_b32 v90, v43 offset:49152
	ds_write_b32 v92, v44 offset:49152
	ds_write_b32 v94, v45 offset:49152
	s_cbranch_scc1 .LBB0_67
; #define LAS __attribute__((address_space(3)))
; __device__ __forceinline__ unsigned pk2(float lo, float hi) { const f32x2c_t v = {lo, hi}; return __builtin_bit_cast(unsigned, __builtin_convertvector(v, bf16x2c_t)); }
; template <int MODE>
; __device__ __forceinline__ void transpose_item(const float* W, int K, int N, bf16_t* WT, const float* gain, LAS float* scr, int item, int lane) {
;     ...
;     const int c = lane & 7;
; #pragma unroll
;     for (int j = 0; j < 4; ++j) { const int n = (lane >> 3) + 8 * j; const LAS float* s = scr + (8 * c) * 33 + n;
;         u32x4 o; o.x = pk2(s[0 * 33], s[1 * 33]); o.y = pk2(s[2 * 33], s[3 * 33]); o.z = pk2(s[4 * 33], s[5 * 33]); o.w = pk2(s[6 * 33], s[7 * 33]);
;         const int drow = inproj_row(n0 + n);
;         *(u32x4*)(WT + (size_t)drow * K + k0 + 8 * c) = o; }
	v_or_b32_e32 v3, v16, v24
	v_lshlrev_b32_e32 v3, 2, v3
	v_lshrrev_b32_e32 v4, 1, v16
	ds_read2_b32 v[32:33], v31 offset0:33 offset1:41
	ds_read2_b32 v[34:35], v31 offset1:8
	ds_read2_b32 v[36:37], v31 offset0:66 offset1:74
	ds_read2_b32 v[38:39], v31 offset0:99 offset1:107
	ds_read2_b32 v[40:41], v31 offset0:132 offset1:140
	ds_read2_b32 v[42:43], v31 offset0:165 offset1:173
	ds_read2_b32 v[44:45], v31 offset0:198 offset1:206
	ds_read2_b32 v[46:47], v31 offset0:231 offset1:239
	v_and_b32_e32 v4, 0x60, v4
	v_bitop3_b32 v7, v16, s24, v24 bitop3:0xc8
	v_and_b32_e32 v3, 0x90, v3
	v_or3_b32 v50, v7, v3, v4
	v_or_b32_e32 v3, v16, v25
	v_lshlrev_b32_e32 v7, 2, v3
	v_ashrrev_i32_e32 v21, 31, v20
	v_ashrrev_i32_e32 v51, 31, v50
	v_and_b32_e32 v7, 0x90, v7
	v_lshl_add_u64 v[48:49], v[20:21], 1, v[14:15]
	v_lshlrev_b64 v[50:51], 11, v[50:51]
	v_and_or_b32 v3, v3, s24, v7
	s_waitcnt lgkmcnt(6)
	v_cvt_pk_bf16_f32 v20, v34, v32
	s_waitcnt lgkmcnt(4)
	v_cvt_pk_bf16_f32 v21, v36, v38
	s_waitcnt lgkmcnt(2)
	v_cvt_pk_bf16_f32 v22, v40, v42
	s_waitcnt lgkmcnt(0)
	v_cvt_pk_bf16_f32 v23, v44, v46
	v_lshl_add_u64 v[50:51], v[48:49], 0, v[50:51]
	v_or3_b32 v32, v3, v4, 4
	v_or_b32_e32 v3, v16, v29
	global_store_dwordx4 v[50:51], v[20:23], off
	v_lshlrev_b32_e32 v7, 2, v3
	v_and_b32_e32 v7, 0x90, v7
	v_cvt_pk_bf16_f32 v20, v35, v33
	v_ashrrev_i32_e32 v33, 31, v32
	v_lshlrev_b64 v[32:33], 11, v[32:33]
	v_cvt_pk_bf16_f32 v21, v37, v39
	v_cvt_pk_bf16_f32 v22, v41, v43
	v_cvt_pk_bf16_f32 v23, v45, v47
	v_lshl_add_u64 v[32:33], v[48:49], 0, v[32:33]
	v_and_or_b32 v3, v3, s24, v7
	ds_read2_b32 v[34:35], v31 offset0:49 offset1:57
	ds_read2_b32 v[36:37], v31 offset0:16 offset1:24
	ds_read2_b32 v[38:39], v31 offset0:82 offset1:90
	ds_read2_b32 v[40:41], v31 offset0:115 offset1:123
	ds_read2_b32 v[42:43], v31 offset0:148 offset1:156
	ds_read2_b32 v[44:45], v31 offset0:181 offset1:189
	ds_read2_b32 v[46:47], v31 offset0:214 offset1:222
	ds_read2_b32 v[50:51], v31 offset0:247 offset1:255
	global_store_dwordx4 v[32:33], v[20:23], off
	v_or3_b32 v32, v3, v4, 8
	v_or_b32_e32 v3, v16, v30
	v_lshlrev_b32_e32 v7, 2, v3
	v_and_b32_e32 v7, 0x90, v7
	v_and_or_b32 v3, v3, s24, v7
	v_ashrrev_i32_e32 v33, 31, v32
	v_or3_b32 v16, v3, v4, 12
	v_lshlrev_b64 v[32:33], 11, v[32:33]
	v_ashrrev_i32_e32 v17, 31, v16
	s_waitcnt lgkmcnt(6)
	v_cvt_pk_bf16_f32 v20, v36, v34
	s_waitcnt lgkmcnt(4)
	v_cvt_pk_bf16_f32 v21, v38, v40
	s_waitcnt lgkmcnt(2)
	v_cvt_pk_bf16_f32 v22, v42, v44
	s_waitcnt lgkmcnt(0)
	v_cvt_pk_bf16_f32 v23, v46, v50
	v_lshl_add_u64 v[32:33], v[48:49], 0, v[32:33]
	v_lshlrev_b64 v[16:17], 11, v[16:17]
	global_store_dwordx4 v[32:33], v[20:23], off
	v_lshl_add_u64 v[16:17], v[48:49], 0, v[16:17]
	s_nop 0
	v_cvt_pk_bf16_f32 v20, v37, v35
	v_cvt_pk_bf16_f32 v21, v39, v41
	v_cvt_pk_bf16_f32 v22, v43, v45
	v_cvt_pk_bf16_f32 v23, v47, v51
	global_store_dwordx4 v[16:17], v[20:23], off
	s_branch .LBB0_54
